# barrier after phase 1 on the short protocol too; phase 1 tile: all 32 x loads issued up front into AGPRs, batch loop straight-lined
# speedup vs baseline: 1.0271x; 1.0000x over previous
.LBB0_160:
	s_lshl_b32 s8, s20, 6
	s_add_i32 s21, s8, 0xffffe000
	v_readlane_b32 s36, v126, 15
	s_cmpk_lt_i32 s20, 0x80
	v_readlane_b32 s37, v126, 16
	v_readlane_b32 s38, v126, 17
	v_readlane_b32 s39, v126, 18
	s_cselect_b32 s1, s37, s39
	s_cselect_b32 s0, s36, s38
	s_ashr_i32 s9, s8, 31
	s_cmpk_lt_i32 s20, 0x80
	s_cselect_b32 s9, s9, 0
	s_cselect_b32 s8, s8, s21
	s_lshr_b32 s21, s21, 11
	s_mulk_i32 s21, 0x1800
	s_addk_i32 s21, 0x1800
	s_cmpk_lt_i32 s20, 0x80
	s_cselect_b32 s22, 0, s21
	s_ashr_i32 s23, s22, 31
	v_lshl_add_u64 v[54:55], s[22:23], 2, v[32:33]
	v_add_co_u32_e32 v12, vcc, s12, v54
	global_load_dwordx4 v[4:7], v[36:37], off
	global_load_dwordx4 v[0:3], v[38:39], off
	v_addc_co_u32_e32 v13, vcc, 0, v55, vcc
	v_add_co_u32_e32 v20, vcc, s13, v54
	global_load_dwordx4 v[8:11], v[54:55], off
	s_nop 0
	global_load_dwordx4 v[12:15], v[12:13], off
	v_addc_co_u32_e32 v21, vcc, 0, v55, vcc
	v_add_co_u32_e32 v28, vcc, s14, v54
	global_load_dwordx4 v[16:19], v[20:21], off offset:-4096
	s_nop 0
	global_load_dwordx4 v[20:23], v[20:21], off
	v_addc_co_u32_e32 v29, vcc, 0, v55, vcc
	v_add_co_u32_e32 v46, vcc, s15, v54
	global_load_dwordx4 v[24:27], v[28:29], off offset:-4096
	s_nop 0
	global_load_dwordx4 v[28:31], v[28:29], off
	v_addc_co_u32_e32 v47, vcc, 0, v55, vcc
	s_waitcnt vmcnt(9)
	v_add_co_u32_e32 v58, vcc, s16, v54
	global_load_dwordx4 v[42:45], v[46:47], off offset:-4096
	s_nop 0
	global_load_dwordx4 v[46:49], v[46:47], off
	v_addc_co_u32_e32 v59, vcc, 0, v55, vcc
	s_waitcnt vmcnt(10)
	v_add_co_u32_e32 v66, vcc, s17, v54
	global_load_dwordx4 v[50:53], v[58:59], off offset:-4096
	s_nop 0
	global_load_dwordx4 v[58:61], v[58:59], off
	v_addc_co_u32_e32 v67, vcc, 0, v55, vcc
	v_add_co_u32_e32 v74, vcc, s18, v54
	global_load_dwordx4 v[62:65], v[66:67], off offset:-4096
	s_nop 0
	global_load_dwordx4 v[66:69], v[66:67], off
	v_addc_co_u32_e32 v75, vcc, 0, v55, vcc
	v_add_co_u32_e32 v54, vcc, s19, v54
	global_load_dwordx4 v[70:73], v[74:75], off offset:-4096
	global_load_dwordx4 v[78:81], v[74:75], off
	v_addc_co_u32_e32 v55, vcc, 0, v55, vcc
	global_load_dwordx4 v[82:85], v[54:55], off offset:-4096
	global_load_dwordx4 v[86:89], v[54:55], off
	s_lshl_b64 s[24:25], s[8:9], 12
	s_add_u32 s24, s24, s0
	s_addc_u32 s25, s25, s1
	v_add_u32_e32 v90, 0xffff2000, v40
	global_load_dwordx4 a[0:3], v90, s[24:25] nt
	v_add_u32_e32 v90, 0x2000, v90
	global_load_dwordx4 a[4:7], v90, s[24:25] nt
	v_add_u32_e32 v90, 0x2000, v90
	global_load_dwordx4 a[8:11], v90, s[24:25] nt
	v_add_u32_e32 v90, 0x2000, v90
	global_load_dwordx4 a[12:15], v90, s[24:25] nt
	v_add_u32_e32 v90, 0x2000, v90
	global_load_dwordx4 a[16:19], v90, s[24:25] nt
	v_add_u32_e32 v90, 0x2000, v90
	global_load_dwordx4 a[20:23], v90, s[24:25] nt
	v_add_u32_e32 v90, 0x2000, v90
	global_load_dwordx4 a[24:27], v90, s[24:25] nt
	v_add_u32_e32 v90, 0x2000, v90
	global_load_dwordx4 a[28:31], v90, s[24:25] nt
	v_add_u32_e32 v90, 0x2000, v90
	global_load_dwordx4 a[32:35], v90, s[24:25] nt
	v_add_u32_e32 v90, 0x2000, v90
	global_load_dwordx4 a[36:39], v90, s[24:25] nt
	v_add_u32_e32 v90, 0x2000, v90
	global_load_dwordx4 a[40:43], v90, s[24:25] nt
	v_add_u32_e32 v90, 0x2000, v90
	global_load_dwordx4 a[44:47], v90, s[24:25] nt
	v_add_u32_e32 v90, 0x2000, v90
	global_load_dwordx4 a[48:51], v90, s[24:25] nt
	v_add_u32_e32 v90, 0x2000, v90
	global_load_dwordx4 a[52:55], v90, s[24:25] nt
	v_add_u32_e32 v90, 0x2000, v90
	global_load_dwordx4 a[56:59], v90, s[24:25] nt
	v_add_u32_e32 v90, 0x2000, v90
	global_load_dwordx4 a[60:63], v90, s[24:25] nt
	v_add_u32_e32 v90, 0x2000, v90
	global_load_dwordx4 a[64:67], v90, s[24:25] nt
	v_add_u32_e32 v90, 0x2000, v90
	global_load_dwordx4 a[68:71], v90, s[24:25] nt
	v_add_u32_e32 v90, 0x2000, v90
	global_load_dwordx4 a[72:75], v90, s[24:25] nt
	v_add_u32_e32 v90, 0x2000, v90
	global_load_dwordx4 a[76:79], v90, s[24:25] nt
	v_add_u32_e32 v90, 0x2000, v90
	global_load_dwordx4 a[80:83], v90, s[24:25] nt
	v_add_u32_e32 v90, 0x2000, v90
	global_load_dwordx4 a[84:87], v90, s[24:25] nt
	v_add_u32_e32 v90, 0x2000, v90
	global_load_dwordx4 a[88:91], v90, s[24:25] nt
	v_add_u32_e32 v90, 0x2000, v90
	global_load_dwordx4 a[92:95], v90, s[24:25] nt
	v_add_u32_e32 v90, 0x2000, v90
	global_load_dwordx4 a[96:99], v90, s[24:25] nt
	v_add_u32_e32 v90, 0x2000, v90
	global_load_dwordx4 a[100:103], v90, s[24:25] nt
	v_add_u32_e32 v90, 0x2000, v90
	global_load_dwordx4 a[104:107], v90, s[24:25] nt
	v_add_u32_e32 v90, 0x2000, v90
	global_load_dwordx4 a[108:111], v90, s[24:25] nt
	v_add_u32_e32 v90, 0x2000, v90
	global_load_dwordx4 a[112:115], v90, s[24:25] nt
	v_add_u32_e32 v90, 0x2000, v90
	global_load_dwordx4 a[116:119], v90, s[24:25] nt
	v_add_u32_e32 v90, 0x2000, v90
	global_load_dwordx4 a[120:123], v90, s[24:25] nt
	v_add_u32_e32 v90, 0x2000, v90
	global_load_dwordx4 a[124:127], v90, s[24:25] nt
	v_lshl_add_u64 v[54:55], s[0:1], 0, v[40:41]
	s_lshl_b64 s[0:1], s[8:9], 12
	v_readlane_b32 s40, v126, 19
	v_readlane_b32 s41, v126, 20
	v_readlane_b32 s42, v126, 21
	v_readlane_b32 s43, v126, 22
	v_readlane_b32 s44, v126, 23
	v_readlane_b32 s45, v126, 24
	v_readlane_b32 s46, v126, 25
	v_readlane_b32 s47, v126, 26
	v_readlane_b32 s48, v126, 27
	v_readlane_b32 s49, v126, 28
	v_readlane_b32 s50, v126, 29
	v_readlane_b32 s51, v126, 30
	s_waitcnt vmcnt(47)
	v_pk_add_f32 v[6:7], v[6:7], v[10:11]
	s_waitcnt vmcnt(46)
	v_pk_add_f32 v[2:3], v[2:3], v[14:15]
	v_pk_add_f32 v[0:1], v[0:1], v[12:13]
	v_pk_add_f32 v[4:5], v[4:5], v[8:9]
	s_waitcnt vmcnt(45)
	v_pk_add_f32 v[6:7], v[6:7], v[18:19]
	s_waitcnt vmcnt(44)
	v_pk_add_f32 v[2:3], v[2:3], v[22:23]
	v_pk_add_f32 v[0:1], v[0:1], v[20:21]
	v_pk_add_f32 v[4:5], v[4:5], v[16:17]
	s_waitcnt vmcnt(43)
	v_pk_add_f32 v[6:7], v[6:7], v[26:27]
	s_waitcnt vmcnt(42)
	v_pk_add_f32 v[2:3], v[2:3], v[30:31]
	v_pk_add_f32 v[0:1], v[0:1], v[28:29]
	v_pk_add_f32 v[4:5], v[4:5], v[24:25]
	s_waitcnt vmcnt(41)
	v_pk_add_f32 v[6:7], v[6:7], v[44:45]
	s_waitcnt vmcnt(40)
	v_pk_add_f32 v[2:3], v[2:3], v[48:49]
	v_pk_add_f32 v[0:1], v[0:1], v[46:47]
	v_pk_add_f32 v[4:5], v[4:5], v[42:43]
	s_waitcnt vmcnt(39)
	v_pk_add_f32 v[6:7], v[6:7], v[52:53]
	s_waitcnt vmcnt(38)
	v_pk_add_f32 v[2:3], v[2:3], v[60:61]
	v_pk_add_f32 v[0:1], v[0:1], v[58:59]
	v_pk_add_f32 v[4:5], v[4:5], v[50:51]
	v_lshl_add_u64 v[50:51], v[54:55], 0, s[0:1]
	s_waitcnt vmcnt(37)
	v_pk_add_f32 v[6:7], v[6:7], v[64:65]
	s_waitcnt vmcnt(36)
	v_pk_add_f32 v[2:3], v[2:3], v[68:69]
	v_pk_add_f32 v[0:1], v[0:1], v[66:67]
	v_pk_add_f32 v[4:5], v[4:5], v[62:63]
	s_mov_b32 s0, -8
	s_waitcnt vmcnt(35)
	v_pk_add_f32 v[6:7], v[6:7], v[72:73]
	s_waitcnt vmcnt(34)
	v_pk_add_f32 v[2:3], v[2:3], v[80:81]
	v_pk_add_f32 v[0:1], v[0:1], v[78:79]
	v_pk_add_f32 v[4:5], v[4:5], v[70:71]
	s_waitcnt vmcnt(32)
	v_pk_add_f32 v[2:3], v[2:3], v[88:89]
	v_pk_add_f32 v[0:1], v[0:1], v[86:87]
	v_pk_add_f32 v[42:43], v[6:7], v[84:85]
	v_pk_add_f32 v[44:45], v[4:5], v[82:83]
	v_pk_add_f32 v[46:47], v[2:3], 1.0 op_sel_hi:[1,0]
	v_pk_add_f32 v[48:49], v[0:1], 1.0 op_sel_hi:[1,0]
	v_mov_b32_e32 v52, v56
	v_ashrrev_i32_e32 v53, 31, v52
	v_add_u32_e32 v54, 2, v52
	v_add_u32_e32 v58, 4, v52
	v_lshlrev_b64 v[70:71], 11, v[52:53]
	v_ashrrev_i32_e32 v55, 31, v54
	v_add_u32_e32 v60, 6, v52
	v_ashrrev_i32_e32 v59, 31, v58
	v_lshl_add_u64 v[70:71], v[34:35], 0, v[70:71]
	v_lshlrev_b64 v[54:55], 11, v[54:55]
	v_add_u32_e32 v62, 8, v52
	v_ashrrev_i32_e32 v61, 31, v60
	v_lshlrev_b64 v[58:59], 11, v[58:59]
	v_lshl_add_u64 v[54:55], v[34:35], 0, v[54:55]
	v_add_u32_e32 v64, 10, v52
	v_ashrrev_i32_e32 v63, 31, v62
	v_lshlrev_b64 v[60:61], 11, v[60:61]
	v_lshl_add_u64 v[58:59], v[34:35], 0, v[58:59]
	v_add_u32_e32 v66, 12, v52
	v_add_u32_e32 v68, 14, v52
	v_ashrrev_i32_e32 v65, 31, v64
	v_lshlrev_b64 v[62:63], 11, v[62:63]
	v_lshl_add_u64 v[60:61], v[34:35], 0, v[60:61]
	v_ashrrev_i32_e32 v67, 31, v66
	v_ashrrev_i32_e32 v69, 31, v68
	v_lshlrev_b64 v[64:65], 11, v[64:65]
	v_lshl_add_u64 v[62:63], v[34:35], 0, v[62:63]
	v_lshlrev_b64 v[66:67], 11, v[66:67]
	v_lshlrev_b64 v[68:69], 11, v[68:69]
	v_lshl_add_u64 v[64:65], v[34:35], 0, v[64:65]
	v_lshl_add_u64 v[66:67], v[34:35], 0, v[66:67]
	v_lshl_add_u64 v[68:69], v[34:35], 0, v[68:69]
	v_add_u32_e32 v52, 16, v52
	s_waitcnt vmcnt(31)
	v_accvgpr_read_b32 v0, a0
	v_accvgpr_read_b32 v1, a1
	v_accvgpr_read_b32 v2, a2
	v_accvgpr_read_b32 v3, a3
	v_pk_fma_f32 v[0:1], v[48:49], v[0:1], v[44:45]
	v_pk_fma_f32 v[2:3], v[46:47], v[2:3], v[42:43]
	v_cvt_pk_bf16_f32 v0, v0, v1
	v_cvt_pk_bf16_f32 v1, v2, v3
	global_store_dwordx2 v[70:71], v[0:1], off
	s_waitcnt vmcnt(31)
	v_accvgpr_read_b32 v4, a4
	v_accvgpr_read_b32 v5, a5
	v_accvgpr_read_b32 v6, a6
	v_accvgpr_read_b32 v7, a7
	v_pk_fma_f32 v[4:5], v[48:49], v[4:5], v[44:45]
	v_pk_fma_f32 v[6:7], v[46:47], v[6:7], v[42:43]
	v_cvt_pk_bf16_f32 v4, v4, v5
	v_cvt_pk_bf16_f32 v5, v6, v7
	global_store_dwordx2 v[54:55], v[4:5], off
	s_waitcnt vmcnt(31)
	v_accvgpr_read_b32 v0, a8
	v_accvgpr_read_b32 v1, a9
	v_accvgpr_read_b32 v2, a10
	v_accvgpr_read_b32 v3, a11
	v_pk_fma_f32 v[0:1], v[48:49], v[0:1], v[44:45]
	v_pk_fma_f32 v[2:3], v[46:47], v[2:3], v[42:43]
	v_cvt_pk_bf16_f32 v0, v0, v1
	v_cvt_pk_bf16_f32 v1, v2, v3
	global_store_dwordx2 v[58:59], v[0:1], off
	s_waitcnt vmcnt(31)
	v_accvgpr_read_b32 v4, a12
	v_accvgpr_read_b32 v5, a13
	v_accvgpr_read_b32 v6, a14
	v_accvgpr_read_b32 v7, a15
	v_pk_fma_f32 v[4:5], v[48:49], v[4:5], v[44:45]
	v_pk_fma_f32 v[6:7], v[46:47], v[6:7], v[42:43]
	v_cvt_pk_bf16_f32 v4, v4, v5
	v_cvt_pk_bf16_f32 v5, v6, v7
	global_store_dwordx2 v[60:61], v[4:5], off
	s_waitcnt vmcnt(31)
	v_accvgpr_read_b32 v0, a16
	v_accvgpr_read_b32 v1, a17
	v_accvgpr_read_b32 v2, a18
	v_accvgpr_read_b32 v3, a19
	v_pk_fma_f32 v[0:1], v[48:49], v[0:1], v[44:45]
	v_pk_fma_f32 v[2:3], v[46:47], v[2:3], v[42:43]
	v_cvt_pk_bf16_f32 v0, v0, v1
	v_cvt_pk_bf16_f32 v1, v2, v3
	global_store_dwordx2 v[62:63], v[0:1], off
	s_waitcnt vmcnt(31)
	v_accvgpr_read_b32 v4, a20
	v_accvgpr_read_b32 v5, a21
	v_accvgpr_read_b32 v6, a22
	v_accvgpr_read_b32 v7, a23
	v_pk_fma_f32 v[4:5], v[48:49], v[4:5], v[44:45]
	v_pk_fma_f32 v[6:7], v[46:47], v[6:7], v[42:43]
	v_cvt_pk_bf16_f32 v4, v4, v5
	v_cvt_pk_bf16_f32 v5, v6, v7
	global_store_dwordx2 v[64:65], v[4:5], off
	s_waitcnt vmcnt(31)
	v_accvgpr_read_b32 v0, a24
	v_accvgpr_read_b32 v1, a25
	v_accvgpr_read_b32 v2, a26
	v_accvgpr_read_b32 v3, a27
	v_pk_fma_f32 v[0:1], v[48:49], v[0:1], v[44:45]
	v_pk_fma_f32 v[2:3], v[46:47], v[2:3], v[42:43]
	v_cvt_pk_bf16_f32 v0, v0, v1
	v_cvt_pk_bf16_f32 v1, v2, v3
	global_store_dwordx2 v[66:67], v[0:1], off
	s_waitcnt vmcnt(31)
	v_accvgpr_read_b32 v4, a28
	v_accvgpr_read_b32 v5, a29
	v_accvgpr_read_b32 v6, a30
	v_accvgpr_read_b32 v7, a31
	v_pk_fma_f32 v[4:5], v[48:49], v[4:5], v[44:45]
	v_pk_fma_f32 v[6:7], v[46:47], v[6:7], v[42:43]
	v_cvt_pk_bf16_f32 v4, v4, v5
	v_cvt_pk_bf16_f32 v5, v6, v7
	global_store_dwordx2 v[68:69], v[4:5], off
	v_ashrrev_i32_e32 v53, 31, v52
	v_add_u32_e32 v54, 2, v52
	v_add_u32_e32 v58, 4, v52
	v_lshlrev_b64 v[70:71], 11, v[52:53]
	v_ashrrev_i32_e32 v55, 31, v54
	v_add_u32_e32 v60, 6, v52
	v_ashrrev_i32_e32 v59, 31, v58
	v_lshl_add_u64 v[70:71], v[34:35], 0, v[70:71]
	v_lshlrev_b64 v[54:55], 11, v[54:55]
	v_add_u32_e32 v62, 8, v52
	v_ashrrev_i32_e32 v61, 31, v60
	v_lshlrev_b64 v[58:59], 11, v[58:59]
	v_lshl_add_u64 v[54:55], v[34:35], 0, v[54:55]
	v_add_u32_e32 v64, 10, v52
	v_ashrrev_i32_e32 v63, 31, v62
	v_lshlrev_b64 v[60:61], 11, v[60:61]
	v_lshl_add_u64 v[58:59], v[34:35], 0, v[58:59]
	v_add_u32_e32 v66, 12, v52
	v_add_u32_e32 v68, 14, v52
	v_ashrrev_i32_e32 v65, 31, v64
	v_lshlrev_b64 v[62:63], 11, v[62:63]
	v_lshl_add_u64 v[60:61], v[34:35], 0, v[60:61]
	v_ashrrev_i32_e32 v67, 31, v66
	v_ashrrev_i32_e32 v69, 31, v68
	v_lshlrev_b64 v[64:65], 11, v[64:65]
	v_lshl_add_u64 v[62:63], v[34:35], 0, v[62:63]
	v_lshlrev_b64 v[66:67], 11, v[66:67]
	v_lshlrev_b64 v[68:69], 11, v[68:69]
	v_lshl_add_u64 v[64:65], v[34:35], 0, v[64:65]
	v_lshl_add_u64 v[66:67], v[34:35], 0, v[66:67]
	v_lshl_add_u64 v[68:69], v[34:35], 0, v[68:69]
	v_add_u32_e32 v52, 16, v52
	s_waitcnt vmcnt(31)
	v_accvgpr_read_b32 v0, a32
	v_accvgpr_read_b32 v1, a33
	v_accvgpr_read_b32 v2, a34
	v_accvgpr_read_b32 v3, a35
	v_pk_fma_f32 v[0:1], v[48:49], v[0:1], v[44:45]
	v_pk_fma_f32 v[2:3], v[46:47], v[2:3], v[42:43]
	v_cvt_pk_bf16_f32 v0, v0, v1
	v_cvt_pk_bf16_f32 v1, v2, v3
	global_store_dwordx2 v[70:71], v[0:1], off
	s_waitcnt vmcnt(31)
	v_accvgpr_read_b32 v4, a36
	v_accvgpr_read_b32 v5, a37
	v_accvgpr_read_b32 v6, a38
	v_accvgpr_read_b32 v7, a39
	v_pk_fma_f32 v[4:5], v[48:49], v[4:5], v[44:45]
	v_pk_fma_f32 v[6:7], v[46:47], v[6:7], v[42:43]
	v_cvt_pk_bf16_f32 v4, v4, v5
	v_cvt_pk_bf16_f32 v5, v6, v7
	global_store_dwordx2 v[54:55], v[4:5], off
	s_waitcnt vmcnt(31)
	v_accvgpr_read_b32 v0, a40
	v_accvgpr_read_b32 v1, a41
	v_accvgpr_read_b32 v2, a42
	v_accvgpr_read_b32 v3, a43
	v_pk_fma_f32 v[0:1], v[48:49], v[0:1], v[44:45]
	v_pk_fma_f32 v[2:3], v[46:47], v[2:3], v[42:43]
	v_cvt_pk_bf16_f32 v0, v0, v1
	v_cvt_pk_bf16_f32 v1, v2, v3
	global_store_dwordx2 v[58:59], v[0:1], off
	s_waitcnt vmcnt(31)
	v_accvgpr_read_b32 v4, a44
	v_accvgpr_read_b32 v5, a45
	v_accvgpr_read_b32 v6, a46
	v_accvgpr_read_b32 v7, a47
	v_pk_fma_f32 v[4:5], v[48:49], v[4:5], v[44:45]
	v_pk_fma_f32 v[6:7], v[46:47], v[6:7], v[42:43]
	v_cvt_pk_bf16_f32 v4, v4, v5
	v_cvt_pk_bf16_f32 v5, v6, v7
	global_store_dwordx2 v[60:61], v[4:5], off
	s_waitcnt vmcnt(31)
	v_accvgpr_read_b32 v0, a48
	v_accvgpr_read_b32 v1, a49
	v_accvgpr_read_b32 v2, a50
	v_accvgpr_read_b32 v3, a51
	v_pk_fma_f32 v[0:1], v[48:49], v[0:1], v[44:45]
	v_pk_fma_f32 v[2:3], v[46:47], v[2:3], v[42:43]
	v_cvt_pk_bf16_f32 v0, v0, v1
	v_cvt_pk_bf16_f32 v1, v2, v3
	global_store_dwordx2 v[62:63], v[0:1], off
	s_waitcnt vmcnt(31)
	v_accvgpr_read_b32 v4, a52
	v_accvgpr_read_b32 v5, a53
	v_accvgpr_read_b32 v6, a54
	v_accvgpr_read_b32 v7, a55
	v_pk_fma_f32 v[4:5], v[48:49], v[4:5], v[44:45]
	v_pk_fma_f32 v[6:7], v[46:47], v[6:7], v[42:43]
	v_cvt_pk_bf16_f32 v4, v4, v5
	v_cvt_pk_bf16_f32 v5, v6, v7
	global_store_dwordx2 v[64:65], v[4:5], off
	s_waitcnt vmcnt(31)
	v_accvgpr_read_b32 v0, a56
	v_accvgpr_read_b32 v1, a57
	v_accvgpr_read_b32 v2, a58
	v_accvgpr_read_b32 v3, a59
	v_pk_fma_f32 v[0:1], v[48:49], v[0:1], v[44:45]
	v_pk_fma_f32 v[2:3], v[46:47], v[2:3], v[42:43]
	v_cvt_pk_bf16_f32 v0, v0, v1
	v_cvt_pk_bf16_f32 v1, v2, v3
	global_store_dwordx2 v[66:67], v[0:1], off
	s_waitcnt vmcnt(31)
	v_accvgpr_read_b32 v4, a60
	v_accvgpr_read_b32 v5, a61
	v_accvgpr_read_b32 v6, a62
	v_accvgpr_read_b32 v7, a63
	v_pk_fma_f32 v[4:5], v[48:49], v[4:5], v[44:45]
	v_pk_fma_f32 v[6:7], v[46:47], v[6:7], v[42:43]
	v_cvt_pk_bf16_f32 v4, v4, v5
	v_cvt_pk_bf16_f32 v5, v6, v7
	global_store_dwordx2 v[68:69], v[4:5], off
	v_ashrrev_i32_e32 v53, 31, v52
	v_add_u32_e32 v54, 2, v52
	v_add_u32_e32 v58, 4, v52
	v_lshlrev_b64 v[70:71], 11, v[52:53]
	v_ashrrev_i32_e32 v55, 31, v54
	v_add_u32_e32 v60, 6, v52
	v_ashrrev_i32_e32 v59, 31, v58
	v_lshl_add_u64 v[70:71], v[34:35], 0, v[70:71]
	v_lshlrev_b64 v[54:55], 11, v[54:55]
	v_add_u32_e32 v62, 8, v52
	v_ashrrev_i32_e32 v61, 31, v60
	v_lshlrev_b64 v[58:59], 11, v[58:59]
	v_lshl_add_u64 v[54:55], v[34:35], 0, v[54:55]
	v_add_u32_e32 v64, 10, v52
	v_ashrrev_i32_e32 v63, 31, v62
	v_lshlrev_b64 v[60:61], 11, v[60:61]
	v_lshl_add_u64 v[58:59], v[34:35], 0, v[58:59]
	v_add_u32_e32 v66, 12, v52
	v_add_u32_e32 v68, 14, v52
	v_ashrrev_i32_e32 v65, 31, v64
	v_lshlrev_b64 v[62:63], 11, v[62:63]
	v_lshl_add_u64 v[60:61], v[34:35], 0, v[60:61]
	v_ashrrev_i32_e32 v67, 31, v66
	v_ashrrev_i32_e32 v69, 31, v68
	v_lshlrev_b64 v[64:65], 11, v[64:65]
	v_lshl_add_u64 v[62:63], v[34:35], 0, v[62:63]
	v_lshlrev_b64 v[66:67], 11, v[66:67]
	v_lshlrev_b64 v[68:69], 11, v[68:69]
	v_lshl_add_u64 v[64:65], v[34:35], 0, v[64:65]
	v_lshl_add_u64 v[66:67], v[34:35], 0, v[66:67]
	v_lshl_add_u64 v[68:69], v[34:35], 0, v[68:69]
	v_add_u32_e32 v52, 16, v52
	s_waitcnt vmcnt(31)
	v_accvgpr_read_b32 v0, a64
	v_accvgpr_read_b32 v1, a65
	v_accvgpr_read_b32 v2, a66
	v_accvgpr_read_b32 v3, a67
	v_pk_fma_f32 v[0:1], v[48:49], v[0:1], v[44:45]
	v_pk_fma_f32 v[2:3], v[46:47], v[2:3], v[42:43]
	v_cvt_pk_bf16_f32 v0, v0, v1
	v_cvt_pk_bf16_f32 v1, v2, v3
	global_store_dwordx2 v[70:71], v[0:1], off
	s_waitcnt vmcnt(31)
	v_accvgpr_read_b32 v4, a68
	v_accvgpr_read_b32 v5, a69
	v_accvgpr_read_b32 v6, a70
	v_accvgpr_read_b32 v7, a71
	v_pk_fma_f32 v[4:5], v[48:49], v[4:5], v[44:45]
	v_pk_fma_f32 v[6:7], v[46:47], v[6:7], v[42:43]
	v_cvt_pk_bf16_f32 v4, v4, v5
	v_cvt_pk_bf16_f32 v5, v6, v7
	global_store_dwordx2 v[54:55], v[4:5], off
	s_waitcnt vmcnt(31)
	v_accvgpr_read_b32 v0, a72
	v_accvgpr_read_b32 v1, a73
	v_accvgpr_read_b32 v2, a74
	v_accvgpr_read_b32 v3, a75
	v_pk_fma_f32 v[0:1], v[48:49], v[0:1], v[44:45]
	v_pk_fma_f32 v[2:3], v[46:47], v[2:3], v[42:43]
	v_cvt_pk_bf16_f32 v0, v0, v1
	v_cvt_pk_bf16_f32 v1, v2, v3
	global_store_dwordx2 v[58:59], v[0:1], off
	s_waitcnt vmcnt(31)
	v_accvgpr_read_b32 v4, a76
	v_accvgpr_read_b32 v5, a77
	v_accvgpr_read_b32 v6, a78
	v_accvgpr_read_b32 v7, a79
	v_pk_fma_f32 v[4:5], v[48:49], v[4:5], v[44:45]
	v_pk_fma_f32 v[6:7], v[46:47], v[6:7], v[42:43]
	v_cvt_pk_bf16_f32 v4, v4, v5
	v_cvt_pk_bf16_f32 v5, v6, v7
	global_store_dwordx2 v[60:61], v[4:5], off
	s_waitcnt vmcnt(31)
	v_accvgpr_read_b32 v0, a80
	v_accvgpr_read_b32 v1, a81
	v_accvgpr_read_b32 v2, a82
	v_accvgpr_read_b32 v3, a83
	v_pk_fma_f32 v[0:1], v[48:49], v[0:1], v[44:45]
	v_pk_fma_f32 v[2:3], v[46:47], v[2:3], v[42:43]
	v_cvt_pk_bf16_f32 v0, v0, v1
	v_cvt_pk_bf16_f32 v1, v2, v3
	global_store_dwordx2 v[62:63], v[0:1], off
	s_waitcnt vmcnt(31)
	v_accvgpr_read_b32 v4, a84
	v_accvgpr_read_b32 v5, a85
	v_accvgpr_read_b32 v6, a86
	v_accvgpr_read_b32 v7, a87
	v_pk_fma_f32 v[4:5], v[48:49], v[4:5], v[44:45]
	v_pk_fma_f32 v[6:7], v[46:47], v[6:7], v[42:43]
	v_cvt_pk_bf16_f32 v4, v4, v5
	v_cvt_pk_bf16_f32 v5, v6, v7
	global_store_dwordx2 v[64:65], v[4:5], off
	s_waitcnt vmcnt(31)
	v_accvgpr_read_b32 v0, a88
	v_accvgpr_read_b32 v1, a89
	v_accvgpr_read_b32 v2, a90
	v_accvgpr_read_b32 v3, a91
	v_pk_fma_f32 v[0:1], v[48:49], v[0:1], v[44:45]
	v_pk_fma_f32 v[2:3], v[46:47], v[2:3], v[42:43]
	v_cvt_pk_bf16_f32 v0, v0, v1
	v_cvt_pk_bf16_f32 v1, v2, v3
	global_store_dwordx2 v[66:67], v[0:1], off
	s_waitcnt vmcnt(31)
	v_accvgpr_read_b32 v4, a92
	v_accvgpr_read_b32 v5, a93
	v_accvgpr_read_b32 v6, a94
	v_accvgpr_read_b32 v7, a95
	v_pk_fma_f32 v[4:5], v[48:49], v[4:5], v[44:45]
	v_pk_fma_f32 v[6:7], v[46:47], v[6:7], v[42:43]
	v_cvt_pk_bf16_f32 v4, v4, v5
	v_cvt_pk_bf16_f32 v5, v6, v7
	global_store_dwordx2 v[68:69], v[4:5], off
	v_ashrrev_i32_e32 v53, 31, v52
	v_add_u32_e32 v54, 2, v52
	v_add_u32_e32 v58, 4, v52
	v_lshlrev_b64 v[70:71], 11, v[52:53]
	v_ashrrev_i32_e32 v55, 31, v54
	v_add_u32_e32 v60, 6, v52
	v_ashrrev_i32_e32 v59, 31, v58
	v_lshl_add_u64 v[70:71], v[34:35], 0, v[70:71]
	v_lshlrev_b64 v[54:55], 11, v[54:55]
	v_add_u32_e32 v62, 8, v52
	v_ashrrev_i32_e32 v61, 31, v60
	v_lshlrev_b64 v[58:59], 11, v[58:59]
	v_lshl_add_u64 v[54:55], v[34:35], 0, v[54:55]
	v_add_u32_e32 v64, 10, v52
	v_ashrrev_i32_e32 v63, 31, v62
	v_lshlrev_b64 v[60:61], 11, v[60:61]
	v_lshl_add_u64 v[58:59], v[34:35], 0, v[58:59]
	v_add_u32_e32 v66, 12, v52
	v_add_u32_e32 v68, 14, v52
	v_ashrrev_i32_e32 v65, 31, v64
	v_lshlrev_b64 v[62:63], 11, v[62:63]
	v_lshl_add_u64 v[60:61], v[34:35], 0, v[60:61]
	v_ashrrev_i32_e32 v67, 31, v66
	v_ashrrev_i32_e32 v69, 31, v68
	v_lshlrev_b64 v[64:65], 11, v[64:65]
	v_lshl_add_u64 v[62:63], v[34:35], 0, v[62:63]
	v_lshlrev_b64 v[66:67], 11, v[66:67]
	v_lshlrev_b64 v[68:69], 11, v[68:69]
	v_lshl_add_u64 v[64:65], v[34:35], 0, v[64:65]
	v_lshl_add_u64 v[66:67], v[34:35], 0, v[66:67]
	v_lshl_add_u64 v[68:69], v[34:35], 0, v[68:69]
	v_add_u32_e32 v52, 16, v52
	s_waitcnt vmcnt(31)
	v_accvgpr_read_b32 v0, a96
	v_accvgpr_read_b32 v1, a97
	v_accvgpr_read_b32 v2, a98
	v_accvgpr_read_b32 v3, a99
	v_pk_fma_f32 v[0:1], v[48:49], v[0:1], v[44:45]
	v_pk_fma_f32 v[2:3], v[46:47], v[2:3], v[42:43]
	v_cvt_pk_bf16_f32 v0, v0, v1
	v_cvt_pk_bf16_f32 v1, v2, v3
	global_store_dwordx2 v[70:71], v[0:1], off
	s_waitcnt vmcnt(31)
	v_accvgpr_read_b32 v4, a100
	v_accvgpr_read_b32 v5, a101
	v_accvgpr_read_b32 v6, a102
	v_accvgpr_read_b32 v7, a103
	v_pk_fma_f32 v[4:5], v[48:49], v[4:5], v[44:45]
	v_pk_fma_f32 v[6:7], v[46:47], v[6:7], v[42:43]
	v_cvt_pk_bf16_f32 v4, v4, v5
	v_cvt_pk_bf16_f32 v5, v6, v7
	global_store_dwordx2 v[54:55], v[4:5], off
	s_waitcnt vmcnt(31)
	v_accvgpr_read_b32 v0, a104
	v_accvgpr_read_b32 v1, a105
	v_accvgpr_read_b32 v2, a106
	v_accvgpr_read_b32 v3, a107
	v_pk_fma_f32 v[0:1], v[48:49], v[0:1], v[44:45]
	v_pk_fma_f32 v[2:3], v[46:47], v[2:3], v[42:43]
	v_cvt_pk_bf16_f32 v0, v0, v1
	v_cvt_pk_bf16_f32 v1, v2, v3
	global_store_dwordx2 v[58:59], v[0:1], off
	s_waitcnt vmcnt(31)
	v_accvgpr_read_b32 v4, a108
	v_accvgpr_read_b32 v5, a109
	v_accvgpr_read_b32 v6, a110
	v_accvgpr_read_b32 v7, a111
	v_pk_fma_f32 v[4:5], v[48:49], v[4:5], v[44:45]
	v_pk_fma_f32 v[6:7], v[46:47], v[6:7], v[42:43]
	v_cvt_pk_bf16_f32 v4, v4, v5
	v_cvt_pk_bf16_f32 v5, v6, v7
	global_store_dwordx2 v[60:61], v[4:5], off
	s_waitcnt vmcnt(31)
	v_accvgpr_read_b32 v0, a112
	v_accvgpr_read_b32 v1, a113
	v_accvgpr_read_b32 v2, a114
	v_accvgpr_read_b32 v3, a115
	v_pk_fma_f32 v[0:1], v[48:49], v[0:1], v[44:45]
	v_pk_fma_f32 v[2:3], v[46:47], v[2:3], v[42:43]
	v_cvt_pk_bf16_f32 v0, v0, v1
	v_cvt_pk_bf16_f32 v1, v2, v3
	global_store_dwordx2 v[62:63], v[0:1], off
	s_waitcnt vmcnt(31)
	v_accvgpr_read_b32 v4, a116
	v_accvgpr_read_b32 v5, a117
	v_accvgpr_read_b32 v6, a118
	v_accvgpr_read_b32 v7, a119
	v_pk_fma_f32 v[4:5], v[48:49], v[4:5], v[44:45]
	v_pk_fma_f32 v[6:7], v[46:47], v[6:7], v[42:43]
	v_cvt_pk_bf16_f32 v4, v4, v5
	v_cvt_pk_bf16_f32 v5, v6, v7
	global_store_dwordx2 v[64:65], v[4:5], off
	s_waitcnt vmcnt(31)
	v_accvgpr_read_b32 v0, a120
	v_accvgpr_read_b32 v1, a121
	v_accvgpr_read_b32 v2, a122
	v_accvgpr_read_b32 v3, a123
	v_pk_fma_f32 v[0:1], v[48:49], v[0:1], v[44:45]
	v_pk_fma_f32 v[2:3], v[46:47], v[2:3], v[42:43]
	v_cvt_pk_bf16_f32 v0, v0, v1
	v_cvt_pk_bf16_f32 v1, v2, v3
	global_store_dwordx2 v[66:67], v[0:1], off
	s_waitcnt vmcnt(31)
	v_accvgpr_read_b32 v4, a124
	v_accvgpr_read_b32 v5, a125
	v_accvgpr_read_b32 v6, a126
	v_accvgpr_read_b32 v7, a127
	v_pk_fma_f32 v[4:5], v[48:49], v[4:5], v[44:45]
	v_pk_fma_f32 v[6:7], v[46:47], v[6:7], v[42:43]
	v_cvt_pk_bf16_f32 v4, v4, v5
	v_cvt_pk_bf16_f32 v5, v6, v7
	global_store_dwordx2 v[68:69], v[4:5], off
	s_add_i32 s20, s20, s3
	s_cmpk_lt_i32 s20, 0x100
	v_add_u32_e32 v56, s10, v56
	s_cbranch_scc1 .LBB0_160
	s_mov_b64 s[52:53], s[84:85]
	s_mov_b64 s[60:61], s[92:93]
	s_mov_b64 s[54:55], s[86:87]
	s_mov_b64 s[56:57], s[88:89]
	s_mov_b64 s[62:63], s[94:95]
	s_mov_b64 s[50:51], s[82:83]
.LBB0_164:
	s_cmp_lt_i32 s91, 3
	s_cbranch_scc1 .LBB0_218
	s_waitcnt vmcnt(0)
	s_waitcnt lgkmcnt(0)
	s_barrier
	s_mov_b64 s[4:5], exec
	v_readlane_b32 s0, v126, 10
	v_readlane_b32 s1, v126, 11
	s_and_b64 s[0:1], s[4:5], s[0:1]
	s_mov_b64 exec, s[0:1]
	s_cbranch_execz .LBB0_217
	v_readlane_b32 s8, v126, 12
	v_readlane_b32 s9, v126, 13
	v_readlane_b32 s3, v126, 14
	v_mov_b32_e32 v0, 0
	v_mov_b32_e32 v1, 1
	s_lshl_b32 s3, s3, 8
	s_add_u32 s0, s8, s3
	s_addc_u32 s1, s9, 0
	s_add_u32 s0, s0, 0x1400
	s_addc_u32 s1, s1, 0
	global_atomic_add v4, v0, v1, s[0:1] sc0
	buffer_inv sc1
	v_mov_b32_e32 v5, 0x23ff0
	ds_read2_b32 v[2:3], v5 offset1:1
	s_add_u32 s8, s8, 0x3400
	s_addc_u32 s9, s9, 0
	s_sub_i32 s3, 2, s90
	s_mov_b32 s7, 0
	s_waitcnt lgkmcnt(0)
	v_readfirstlane_b32 s1, v2
	v_readfirstlane_b32 s6, v3
	s_mul_i32 s1, s1, s3
	s_mul_i32 s6, s6, s3
	s_waitcnt vmcnt(1)
	v_readfirstlane_b32 s0, v4
	s_add_i32 s0, s0, 1
	s_cmp_lg_u32 s0, s1
	s_cbranch_scc1 .Lgb1_poll
	buffer_wbl2 sc1
	s_waitcnt vmcnt(0)
	global_atomic_add v0, v1, s[8:9]

.Lgb1_rel:
.LBB0_217:
	s_or_b64 exec, exec, s[4:5]
	s_waitcnt lgkmcnt(0)
	s_barrier
.LBB0_218:
	s_cmp_lt_i32 s90, 3
	s_cselect_b64 s[0:1], -1, 0
	s_cmp_gt_i32 s91, 2
	s_cselect_b64 s[4:5], -1, 0
	s_and_b64 s[0:1], s[0:1], s[4:5]
	s_andn2_b64 vcc, exec, s[0:1]
	s_cbranch_vccnz .LBB0_384
	s_add_u32 s10, s96, 0x128
	s_addc_u32 s11, s97, 0
	v_mov_b32_e32 v0, v77
	s_cmpk_lt_i32 s2, 0x200
	s_cselect_b64 s[0:1], -1, 0
	s_cmpk_gt_i32 s2, 0x1ff
	v_readfirstlane_b32 s26, v0
	s_cbranch_scc0 .LBB0_222
	s_waitcnt lgkmcnt(0)
	s_load_dword s3, s[96:97], 0x128
	s_andn2_b64 vcc, exec, s[0:1]
	s_cbranch_vccz .LBB0_227
